# v17 plus chunk-local state MFMA loop: fragments of 8 K-steps loaded ahead (was load-wait-mfma per step)
# baseline (speedup 1.0000x reference)
; __device__ __forceinline__ void ssm_local(const Params& P, int item, int lane) {
;     const int rt = item & 3, cg_ = (item >> 2) & 15, g = item >> 6, r32 = lane & 31, hi = lane >> 5;
;     const bf16_t* F = (const bf16_t*)(P.ws + WS_FTAB) + ((size_t)g * 128 + rt * 32 + r32) * 1024 + hi * 8;
;     const bf16_t* U = (const bf16_t*)(P.ws + WS_U) + ((size_t)(cg_ * 32 + r32) * 64) * 1024 + g * 16 + hi * 8;
;     f32x16 acc = {};
; #pragma unroll 16
;     for (int s = 0; s < 64; ++s) { const bf16x8 a = *(const bf16x8*)(F + s * 16); const bf16x8 b = *(const bf16x8*)(U + (size_t)s * 1024);
;         acc = __builtin_amdgcn_mfma_f32_32x32x16_bf16(a, b, acc, 0, 0, 0); }
.LBB0_253:
	s_ashr_i32 s14, s0, 6
	s_ashr_i32 s15, s14, 31
	s_lshl_b64 s[16:17], s[14:15], 7
	s_lshl_b32 s18, s14, 4
	s_and_b32 s4, s1, 0x60
	s_lshl_b32 s9, s8, 17
	s_ashr_i32 s19, s18, 31
	v_or_b32_e32 v0, s16, v16
	s_and_b32 s9, s9, 0x3c00000
	v_mov_b32_e32 v1, s17
	v_or_b32_e32 v0, s4, v0
	s_lshl_b64 s[16:17], s[18:19], 1
	v_lshlrev_b64 v[0:1], 11, v[0:1]
	s_add_u32 s16, s2, s16
	v_lshl_or_b32 v162, v17, 11, s9
	v_lshl_add_u64 v[22:23], s[2:3], 0, v[0:1]
	s_addc_u32 s17, s3, s17
	v_mov_b32_e32 v0, 0
	v_lshl_add_u64 v[24:25], s[16:17], 0, v[162:163]
	s_mov_b32 s9, 64
	v_mov_b32_e32 v1, v0
	v_mov_b32_e32 v2, v0
	v_mov_b32_e32 v3, v0
	v_mov_b32_e32 v4, v0
	v_mov_b32_e32 v5, v0
	v_mov_b32_e32 v6, v0
	v_mov_b32_e32 v7, v0
	v_mov_b32_e32 v8, v0
	v_mov_b32_e32 v9, v0
	v_mov_b32_e32 v10, v0
	v_mov_b32_e32 v11, v0
	v_mov_b32_e32 v12, v0
	v_mov_b32_e32 v13, v0
	v_mov_b32_e32 v14, v0
	v_mov_b32_e32 v15, v0
	v_lshl_add_u64 v[26:27], v[22:23], 0, v[18:19]
	s_mov_b64 s[16:17], 0x3e700000
	v_lshl_add_u64 v[26:27], v[26:27], 0, s[16:17]
	v_lshl_add_u64 v[38:39], v[24:25], 0, v[18:19]
	s_mov_b64 s[16:17], 0x15400000
	v_lshl_add_u64 v[38:39], v[38:39], 0, s[16:17]
	s_mov_b64 s[16:17], 0x1000
	global_load_dwordx4 v[40:43], v[26:27], off
	global_load_dwordx4 v[72:75], v[38:39], off
	global_load_dwordx4 v[44:47], v[26:27], off offset:32
	global_load_dwordx4 v[76:79], v[38:39], off offset:2048
	v_lshl_add_u64 v[38:39], v[38:39], 0, s[16:17]
	global_load_dwordx4 v[48:51], v[26:27], off offset:64
	global_load_dwordx4 v[80:83], v[38:39], off
	global_load_dwordx4 v[52:55], v[26:27], off offset:96
	global_load_dwordx4 v[84:87], v[38:39], off offset:2048
	v_lshl_add_u64 v[38:39], v[38:39], 0, s[16:17]
	global_load_dwordx4 v[56:59], v[26:27], off offset:128
	global_load_dwordx4 v[88:91], v[38:39], off
	global_load_dwordx4 v[60:63], v[26:27], off offset:160
	global_load_dwordx4 v[92:95], v[38:39], off offset:2048
	v_lshl_add_u64 v[38:39], v[38:39], 0, s[16:17]
	global_load_dwordx4 v[64:67], v[26:27], off offset:192
	global_load_dwordx4 v[96:99], v[38:39], off
	global_load_dwordx4 v[68:71], v[26:27], off offset:224
	global_load_dwordx4 v[100:103], v[38:39], off offset:2048
	v_lshl_add_u64 v[38:39], v[38:39], 0, s[16:17]
	global_load_dwordx4 v[104:107], v[26:27], off offset:256
	global_load_dwordx4 v[136:139], v[38:39], off
	global_load_dwordx4 v[108:111], v[26:27], off offset:288
	global_load_dwordx4 v[140:143], v[38:39], off offset:2048
	v_lshl_add_u64 v[38:39], v[38:39], 0, s[16:17]
	global_load_dwordx4 v[112:115], v[26:27], off offset:320
	global_load_dwordx4 v[164:167], v[38:39], off
	global_load_dwordx4 v[116:119], v[26:27], off offset:352
	global_load_dwordx4 v[168:171], v[38:39], off offset:2048
	v_lshl_add_u64 v[38:39], v[38:39], 0, s[16:17]
	global_load_dwordx4 v[120:123], v[26:27], off offset:384
	global_load_dwordx4 v[182:185], v[38:39], off
	global_load_dwordx4 v[124:127], v[26:27], off offset:416
	global_load_dwordx4 v[188:191], v[38:39], off offset:2048
	v_lshl_add_u64 v[38:39], v[38:39], 0, s[16:17]
	global_load_dwordx4 v[128:131], v[26:27], off offset:448
	global_load_dwordx4 v[194:197], v[38:39], off
	global_load_dwordx4 v[132:135], v[26:27], off offset:480
	global_load_dwordx4 v[198:201], v[38:39], off offset:2048
	v_lshl_add_u64 v[38:39], v[38:39], 0, s[16:17]
	s_waitcnt vmcnt(30)
	v_mfma_f32_32x32x16_bf16 v[0:15], v[40:43], v[72:75], v[0:15]
	s_waitcnt vmcnt(28)
	v_mfma_f32_32x32x16_bf16 v[0:15], v[44:47], v[76:79], v[0:15]
	s_waitcnt vmcnt(26)
	v_mfma_f32_32x32x16_bf16 v[0:15], v[48:51], v[80:83], v[0:15]
	s_waitcnt vmcnt(24)
	v_mfma_f32_32x32x16_bf16 v[0:15], v[52:55], v[84:87], v[0:15]
	s_waitcnt vmcnt(22)
	v_mfma_f32_32x32x16_bf16 v[0:15], v[56:59], v[88:91], v[0:15]
	s_waitcnt vmcnt(20)
	v_mfma_f32_32x32x16_bf16 v[0:15], v[60:63], v[92:95], v[0:15]
	s_waitcnt vmcnt(18)
	v_mfma_f32_32x32x16_bf16 v[0:15], v[64:67], v[96:99], v[0:15]
	s_waitcnt vmcnt(16)
	v_mfma_f32_32x32x16_bf16 v[0:15], v[68:71], v[100:103], v[0:15]
	global_load_dwordx4 v[40:43], v[26:27], off offset:512
	global_load_dwordx4 v[72:75], v[38:39], off
	global_load_dwordx4 v[44:47], v[26:27], off offset:544
	global_load_dwordx4 v[76:79], v[38:39], off offset:2048
	v_lshl_add_u64 v[38:39], v[38:39], 0, s[16:17]
	global_load_dwordx4 v[48:51], v[26:27], off offset:576
	global_load_dwordx4 v[80:83], v[38:39], off
	global_load_dwordx4 v[52:55], v[26:27], off offset:608
	global_load_dwordx4 v[84:87], v[38:39], off offset:2048
	v_lshl_add_u64 v[38:39], v[38:39], 0, s[16:17]
	global_load_dwordx4 v[56:59], v[26:27], off offset:640
	global_load_dwordx4 v[88:91], v[38:39], off
	global_load_dwordx4 v[60:63], v[26:27], off offset:672
	global_load_dwordx4 v[92:95], v[38:39], off offset:2048
	v_lshl_add_u64 v[38:39], v[38:39], 0, s[16:17]
	global_load_dwordx4 v[64:67], v[26:27], off offset:704
	global_load_dwordx4 v[96:99], v[38:39], off
	global_load_dwordx4 v[68:71], v[26:27], off offset:736
	global_load_dwordx4 v[100:103], v[38:39], off offset:2048
	v_lshl_add_u64 v[38:39], v[38:39], 0, s[16:17]
	s_waitcnt vmcnt(30)
	v_mfma_f32_32x32x16_bf16 v[0:15], v[104:107], v[136:139], v[0:15]
	s_waitcnt vmcnt(28)
	v_mfma_f32_32x32x16_bf16 v[0:15], v[108:111], v[140:143], v[0:15]
	s_waitcnt vmcnt(26)
	v_mfma_f32_32x32x16_bf16 v[0:15], v[112:115], v[164:167], v[0:15]
	s_waitcnt vmcnt(24)
	v_mfma_f32_32x32x16_bf16 v[0:15], v[116:119], v[168:171], v[0:15]
	s_waitcnt vmcnt(22)
	v_mfma_f32_32x32x16_bf16 v[0:15], v[120:123], v[182:185], v[0:15]
	s_waitcnt vmcnt(20)
	v_mfma_f32_32x32x16_bf16 v[0:15], v[124:127], v[188:191], v[0:15]
	s_waitcnt vmcnt(18)
	v_mfma_f32_32x32x16_bf16 v[0:15], v[128:131], v[194:197], v[0:15]
	s_waitcnt vmcnt(16)
; __device__ __forceinline__ void ssm_local(const Params& P, int item, int lane) {
;     ...
;     for (int s = 0; s < 64; ++s) { const bf16x8 a = *(const bf16x8*)(F + s * 16); const bf16x8 b = *(const bf16x8*)(U + (size_t)s * 1024);
;         acc = __builtin_amdgcn_mfma_f32_32x32x16_bf16(a, b, acc, 0, 0, 0); }
	v_mfma_f32_32x32x16_bf16 v[0:15], v[132:135], v[198:201], v[0:15]
	global_load_dwordx4 v[104:107], v[26:27], off offset:768
	global_load_dwordx4 v[136:139], v[38:39], off
	global_load_dwordx4 v[108:111], v[26:27], off offset:800
	global_load_dwordx4 v[140:143], v[38:39], off offset:2048
	v_lshl_add_u64 v[38:39], v[38:39], 0, s[16:17]
	global_load_dwordx4 v[112:115], v[26:27], off offset:832
	global_load_dwordx4 v[164:167], v[38:39], off
	global_load_dwordx4 v[116:119], v[26:27], off offset:864
	global_load_dwordx4 v[168:171], v[38:39], off offset:2048
	v_lshl_add_u64 v[38:39], v[38:39], 0, s[16:17]
	global_load_dwordx4 v[120:123], v[26:27], off offset:896
	global_load_dwordx4 v[182:185], v[38:39], off
	global_load_dwordx4 v[124:127], v[26:27], off offset:928
	global_load_dwordx4 v[188:191], v[38:39], off offset:2048
	v_lshl_add_u64 v[38:39], v[38:39], 0, s[16:17]
	global_load_dwordx4 v[128:131], v[26:27], off offset:960
	global_load_dwordx4 v[194:197], v[38:39], off
	global_load_dwordx4 v[132:135], v[26:27], off offset:992
	global_load_dwordx4 v[198:201], v[38:39], off offset:2048
	v_lshl_add_u64 v[38:39], v[38:39], 0, s[16:17]
	s_waitcnt vmcnt(30)
	v_mfma_f32_32x32x16_bf16 v[0:15], v[40:43], v[72:75], v[0:15]
	s_waitcnt vmcnt(28)
	v_mfma_f32_32x32x16_bf16 v[0:15], v[44:47], v[76:79], v[0:15]
	s_waitcnt vmcnt(26)
	v_mfma_f32_32x32x16_bf16 v[0:15], v[48:51], v[80:83], v[0:15]
	s_waitcnt vmcnt(24)
	v_mfma_f32_32x32x16_bf16 v[0:15], v[52:55], v[84:87], v[0:15]
	s_waitcnt vmcnt(22)
	v_mfma_f32_32x32x16_bf16 v[0:15], v[56:59], v[88:91], v[0:15]
	s_waitcnt vmcnt(20)
	v_mfma_f32_32x32x16_bf16 v[0:15], v[60:63], v[92:95], v[0:15]
	s_waitcnt vmcnt(18)
	v_mfma_f32_32x32x16_bf16 v[0:15], v[64:67], v[96:99], v[0:15]
	s_waitcnt vmcnt(16)
	v_mfma_f32_32x32x16_bf16 v[0:15], v[68:71], v[100:103], v[0:15]
	global_load_dwordx4 v[40:43], v[26:27], off offset:1024
	global_load_dwordx4 v[72:75], v[38:39], off
	global_load_dwordx4 v[44:47], v[26:27], off offset:1056
	global_load_dwordx4 v[76:79], v[38:39], off offset:2048
	v_lshl_add_u64 v[38:39], v[38:39], 0, s[16:17]
	global_load_dwordx4 v[48:51], v[26:27], off offset:1088
	global_load_dwordx4 v[80:83], v[38:39], off
	global_load_dwordx4 v[52:55], v[26:27], off offset:1120
	global_load_dwordx4 v[84:87], v[38:39], off offset:2048
	v_lshl_add_u64 v[38:39], v[38:39], 0, s[16:17]
	global_load_dwordx4 v[56:59], v[26:27], off offset:1152
	global_load_dwordx4 v[88:91], v[38:39], off
	global_load_dwordx4 v[60:63], v[26:27], off offset:1184
	global_load_dwordx4 v[92:95], v[38:39], off offset:2048
	v_lshl_add_u64 v[38:39], v[38:39], 0, s[16:17]
	global_load_dwordx4 v[64:67], v[26:27], off offset:1216
	global_load_dwordx4 v[96:99], v[38:39], off
	global_load_dwordx4 v[68:71], v[26:27], off offset:1248
	global_load_dwordx4 v[100:103], v[38:39], off offset:2048
	v_lshl_add_u64 v[38:39], v[38:39], 0, s[16:17]
	s_waitcnt vmcnt(30)
	v_mfma_f32_32x32x16_bf16 v[0:15], v[104:107], v[136:139], v[0:15]
	s_waitcnt vmcnt(28)
	v_mfma_f32_32x32x16_bf16 v[0:15], v[108:111], v[140:143], v[0:15]
	s_waitcnt vmcnt(26)
	v_mfma_f32_32x32x16_bf16 v[0:15], v[112:115], v[164:167], v[0:15]
	s_waitcnt vmcnt(24)
	v_mfma_f32_32x32x16_bf16 v[0:15], v[116:119], v[168:171], v[0:15]
	s_waitcnt vmcnt(22)
	v_mfma_f32_32x32x16_bf16 v[0:15], v[120:123], v[182:185], v[0:15]
	s_waitcnt vmcnt(20)
	v_mfma_f32_32x32x16_bf16 v[0:15], v[124:127], v[188:191], v[0:15]
	s_waitcnt vmcnt(18)
	v_mfma_f32_32x32x16_bf16 v[0:15], v[128:131], v[194:197], v[0:15]
	s_waitcnt vmcnt(16)
	v_mfma_f32_32x32x16_bf16 v[0:15], v[132:135], v[198:201], v[0:15]
	global_load_dwordx4 v[104:107], v[26:27], off offset:1280
	global_load_dwordx4 v[136:139], v[38:39], off
	global_load_dwordx4 v[108:111], v[26:27], off offset:1312
	global_load_dwordx4 v[140:143], v[38:39], off offset:2048
	v_lshl_add_u64 v[38:39], v[38:39], 0, s[16:17]
	global_load_dwordx4 v[112:115], v[26:27], off offset:1344
	global_load_dwordx4 v[164:167], v[38:39], off
	global_load_dwordx4 v[116:119], v[26:27], off offset:1376
	global_load_dwordx4 v[168:171], v[38:39], off offset:2048
	v_lshl_add_u64 v[38:39], v[38:39], 0, s[16:17]
	global_load_dwordx4 v[120:123], v[26:27], off offset:1408
	global_load_dwordx4 v[182:185], v[38:39], off
	global_load_dwordx4 v[124:127], v[26:27], off offset:1440
	global_load_dwordx4 v[188:191], v[38:39], off offset:2048
	v_lshl_add_u64 v[38:39], v[38:39], 0, s[16:17]
	global_load_dwordx4 v[128:131], v[26:27], off offset:1472
	global_load_dwordx4 v[194:197], v[38:39], off
	global_load_dwordx4 v[132:135], v[26:27], off offset:1504
	global_load_dwordx4 v[198:201], v[38:39], off offset:2048
	v_lshl_add_u64 v[38:39], v[38:39], 0, s[16:17]
	s_waitcnt vmcnt(30)
	v_mfma_f32_32x32x16_bf16 v[0:15], v[40:43], v[72:75], v[0:15]
	s_waitcnt vmcnt(28)
	v_mfma_f32_32x32x16_bf16 v[0:15], v[44:47], v[76:79], v[0:15]
	s_waitcnt vmcnt(26)
	v_mfma_f32_32x32x16_bf16 v[0:15], v[48:51], v[80:83], v[0:15]
	s_waitcnt vmcnt(24)
	v_mfma_f32_32x32x16_bf16 v[0:15], v[52:55], v[84:87], v[0:15]
	s_waitcnt vmcnt(22)
	v_mfma_f32_32x32x16_bf16 v[0:15], v[56:59], v[88:91], v[0:15]
	s_waitcnt vmcnt(20)
; __device__ __forceinline__ void ssm_local(const Params& P, int item, int lane) {
;     ...
;     for (int s = 0; s < 64; ++s) { const bf16x8 a = *(const bf16x8*)(F + s * 16); const bf16x8 b = *(const bf16x8*)(U + (size_t)s * 1024);
;         acc = __builtin_amdgcn_mfma_f32_32x32x16_bf16(a, b, acc, 0, 0, 0); }
;     float* xl = (float*)(P.ws + WS_XLOC) + ((size_t)(cg_ * 32 + r32) * 64 + g) * 128 + rt * 32 + 4 * hi;
; #pragma unroll
;     for (int q = 0; q < 4; ++q) *(f32x4*)(xl + 8 * q) = (f32x4){acc[4 * q], acc[4 * q + 1], acc[4 * q + 2], acc[4 * q + 3]};
	v_mfma_f32_32x32x16_bf16 v[0:15], v[60:63], v[92:95], v[0:15]
	s_waitcnt vmcnt(18)
	v_mfma_f32_32x32x16_bf16 v[0:15], v[64:67], v[96:99], v[0:15]
	s_waitcnt vmcnt(16)
	v_mfma_f32_32x32x16_bf16 v[0:15], v[68:71], v[100:103], v[0:15]
	global_load_dwordx4 v[40:43], v[26:27], off offset:1536
	global_load_dwordx4 v[72:75], v[38:39], off
	global_load_dwordx4 v[44:47], v[26:27], off offset:1568
	global_load_dwordx4 v[76:79], v[38:39], off offset:2048
	v_lshl_add_u64 v[38:39], v[38:39], 0, s[16:17]
	global_load_dwordx4 v[48:51], v[26:27], off offset:1600
	global_load_dwordx4 v[80:83], v[38:39], off
	global_load_dwordx4 v[52:55], v[26:27], off offset:1632
	global_load_dwordx4 v[84:87], v[38:39], off offset:2048
	v_lshl_add_u64 v[38:39], v[38:39], 0, s[16:17]
	global_load_dwordx4 v[56:59], v[26:27], off offset:1664
	global_load_dwordx4 v[88:91], v[38:39], off
	global_load_dwordx4 v[60:63], v[26:27], off offset:1696
	global_load_dwordx4 v[92:95], v[38:39], off offset:2048
	v_lshl_add_u64 v[38:39], v[38:39], 0, s[16:17]
	global_load_dwordx4 v[64:67], v[26:27], off offset:1728
	global_load_dwordx4 v[96:99], v[38:39], off
	global_load_dwordx4 v[68:71], v[26:27], off offset:1760
	global_load_dwordx4 v[100:103], v[38:39], off offset:2048
	v_lshl_add_u64 v[38:39], v[38:39], 0, s[16:17]
	s_waitcnt vmcnt(30)
	v_mfma_f32_32x32x16_bf16 v[0:15], v[104:107], v[136:139], v[0:15]
	s_waitcnt vmcnt(28)
	v_mfma_f32_32x32x16_bf16 v[0:15], v[108:111], v[140:143], v[0:15]
	s_waitcnt vmcnt(26)
	v_mfma_f32_32x32x16_bf16 v[0:15], v[112:115], v[164:167], v[0:15]
	s_waitcnt vmcnt(24)
	v_mfma_f32_32x32x16_bf16 v[0:15], v[116:119], v[168:171], v[0:15]
	s_waitcnt vmcnt(22)
	v_mfma_f32_32x32x16_bf16 v[0:15], v[120:123], v[182:185], v[0:15]
	s_waitcnt vmcnt(20)
	v_mfma_f32_32x32x16_bf16 v[0:15], v[124:127], v[188:191], v[0:15]
	s_waitcnt vmcnt(18)
	v_mfma_f32_32x32x16_bf16 v[0:15], v[128:131], v[194:197], v[0:15]
	s_waitcnt vmcnt(16)
	v_mfma_f32_32x32x16_bf16 v[0:15], v[132:135], v[198:201], v[0:15]
	global_load_dwordx4 v[104:107], v[26:27], off offset:1792
	global_load_dwordx4 v[136:139], v[38:39], off
	global_load_dwordx4 v[108:111], v[26:27], off offset:1824
	global_load_dwordx4 v[140:143], v[38:39], off offset:2048
	v_lshl_add_u64 v[38:39], v[38:39], 0, s[16:17]
	global_load_dwordx4 v[112:115], v[26:27], off offset:1856
	global_load_dwordx4 v[164:167], v[38:39], off
	global_load_dwordx4 v[116:119], v[26:27], off offset:1888
	global_load_dwordx4 v[168:171], v[38:39], off offset:2048
	v_lshl_add_u64 v[38:39], v[38:39], 0, s[16:17]
	global_load_dwordx4 v[120:123], v[26:27], off offset:1920
	global_load_dwordx4 v[182:185], v[38:39], off
	global_load_dwordx4 v[124:127], v[26:27], off offset:1952
	global_load_dwordx4 v[188:191], v[38:39], off offset:2048
	v_lshl_add_u64 v[38:39], v[38:39], 0, s[16:17]
	global_load_dwordx4 v[128:131], v[26:27], off offset:1984
	global_load_dwordx4 v[194:197], v[38:39], off
	global_load_dwordx4 v[132:135], v[26:27], off offset:2016
	global_load_dwordx4 v[198:201], v[38:39], off offset:2048
	s_waitcnt vmcnt(30)
	v_mfma_f32_32x32x16_bf16 v[0:15], v[40:43], v[72:75], v[0:15]
	s_waitcnt vmcnt(28)
	v_mfma_f32_32x32x16_bf16 v[0:15], v[44:47], v[76:79], v[0:15]
	s_waitcnt vmcnt(26)
	v_mfma_f32_32x32x16_bf16 v[0:15], v[48:51], v[80:83], v[0:15]
	s_waitcnt vmcnt(24)
	v_mfma_f32_32x32x16_bf16 v[0:15], v[52:55], v[84:87], v[0:15]
	s_waitcnt vmcnt(22)
	v_mfma_f32_32x32x16_bf16 v[0:15], v[56:59], v[88:91], v[0:15]
	s_waitcnt vmcnt(20)
	v_mfma_f32_32x32x16_bf16 v[0:15], v[60:63], v[92:95], v[0:15]
	s_waitcnt vmcnt(18)
	v_mfma_f32_32x32x16_bf16 v[0:15], v[64:67], v[96:99], v[0:15]
	s_waitcnt vmcnt(16)
	v_mfma_f32_32x32x16_bf16 v[0:15], v[68:71], v[100:103], v[0:15]
	s_waitcnt vmcnt(14)
	v_mfma_f32_32x32x16_bf16 v[0:15], v[104:107], v[136:139], v[0:15]
	s_waitcnt vmcnt(12)
	v_mfma_f32_32x32x16_bf16 v[0:15], v[108:111], v[140:143], v[0:15]
	s_waitcnt vmcnt(10)
	v_mfma_f32_32x32x16_bf16 v[0:15], v[112:115], v[164:167], v[0:15]
	s_waitcnt vmcnt(8)
	v_mfma_f32_32x32x16_bf16 v[0:15], v[116:119], v[168:171], v[0:15]
	s_waitcnt vmcnt(6)
	v_mfma_f32_32x32x16_bf16 v[0:15], v[120:123], v[182:185], v[0:15]
	s_waitcnt vmcnt(4)
	v_mfma_f32_32x32x16_bf16 v[0:15], v[124:127], v[188:191], v[0:15]
	s_waitcnt vmcnt(2)
	v_mfma_f32_32x32x16_bf16 v[0:15], v[128:131], v[194:197], v[0:15]
	s_waitcnt vmcnt(0)
	v_mfma_f32_32x32x16_bf16 v[0:15], v[132:135], v[198:201], v[0:15]
	s_lshl_b32 s4, s0, 3
	s_and_b32 s4, s4, 0x1e0
	v_or_b32_e32 v21, s4, v16
	v_lshlrev_b32_e32 v162, 6, v21
	v_lshl_add_u64 v[22:23], v[162:163], 0, s[14:15]
	v_lshlrev_b64 v[22:23], 9, v[22:23]
	s_lshl_b32 s4, s0, 7
	v_lshl_add_u64 v[22:23], s[6:7], 0, v[22:23]
	s_and_b32 s10, s4, 0x180
	v_lshl_add_u64 v[22:23], v[22:23], 0, s[10:11]
	v_mov_b32_e32 v21, v163
	s_add_i32 s0, s0, s56
	s_add_i32 s1, s1, s26
	s_add_i32 s8, s8, s31
	v_lshl_add_u64 v[22:23], v[22:23], 0, v[20:21]
	s_cmpk_gt_i32 s0, 0xfff
	flat_store_dwordx4 v[22:23], v[0:3]
	flat_store_dwordx4 v[22:23], v[4:7] offset:32
	flat_store_dwordx4 v[22:23], v[8:11] offset:64
	flat_store_dwordx4 v[22:23], v[12:15] offset:96
	s_cbranch_scc0 .LBB0_253
